# adds: v_pk_add_f32 in softmax row-sum split into scalar v_add_f32 (bit-identical)
# baseline (speedup 1.0000x reference)
; #define MFMA32(a, b, c) __builtin_amdgcn_mfma_f32_32x32x16_bf16((a), (b), (c), 0, 0, 0)
; #define VLOAD(dst, sbv, q) do { _Pragma("unroll") for (int d_ = 0; d_ < 4; ++d_) dst[d_] = *(const lds_bf16x8*)((sbv) + vo[q] + d_ * 4096); } while (0)
; #define FENCE __builtin_amdgcn_sched_barrier(0)
; DI void diff_unit(KP p, int l, int b, int h, int qb, int isctx, float lamv, float lam_init, char* ldsc) {
;     ...
;   for (int kt = 0; kt < nt - 1; ++kt) {
;     asm volatile("s_waitcnt vmcnt(0)" ::: "memory");
;     __builtin_amdgcn_s_barrier();
;     const int stg1 = stg == 2 ? 0 : stg + 1;
;     if (kt + 2 < nt) { const int s2_ = stg >= 1 ? stg - 1 : 2; DISSUE(kt + 2, s2_); }
;     if (need) {
; #pragma unroll
;       for (int d = 0; d < 4; ++d) o[d] *= alpha;
;     }
;     const lds_u8* sbv = L + stg * STG + 16384;
;     const lds_u8* sbk = L + stg1 * STG + comp * 8192;
;     bf16x8 kf[2][4];
;     f32x16 st[2];
; #pragma unroll
;     for (int t = 0; t < 2; ++t)
; #pragma unroll
;       for (int ks = 0; ks < 4; ++ks) kf[t][ks] = *(const lds_bf16x8*)(sbk + ko[ks] + t * 4096);
;     FENCE;
;     pv_grp(o, vA, P[0]); pv_grp(o, vB, P[1]);
;     VLOAD(vA, sbv, 2); VLOAD(vB, sbv, 3);
;     FENCE;
; #pragma unroll
;     for (int i = 0; i < 16; ++i) { st[0][i] = 0.f; st[1][i] = 0.f; }
; #pragma unroll
;     for (int ks = 0; ks < 4; ++ks) st[0] = MFMA32(kf[0][ks], qf[ks], st[0]);
; #pragma unroll
;     for (int ks = 0; ks < 4; ++ks) st[1] = MFMA32(kf[1][ks], qf[ks], st[1]);
;     FENCE;
.LBB0_477:
	s_add_i32 s2, s17, 1
	s_and_b32 s16, s2, 3
	s_lshl_b32 s2, s16, 15
	s_add_i32 s15, s2, 0
	s_add_i32 s2, s15, s14
	v_add_u32_e32 v0, s2, v141
	v_add_u32_e32 v140, s2, v145
	v_add_u32_e32 v191, s2, v147
	v_add_u32_e32 v216, s2, v148
	ds_read_b128 v[154:157], v0
	ds_read_b128 v[192:195], v0 offset:4096
	ds_read_b128 v[196:199], v140
	ds_read_b128 v[200:203], v140 offset:4096
	ds_read_b128 v[204:207], v191
	ds_read_b128 v[208:211], v191 offset:4096
	ds_read_b128 v[212:215], v216
	ds_read_b128 v[216:219], v216 offset:4096
	s_lshl_b32 s2, s17, 15
	s_add_i32 s2, s2, 0
	s_waitcnt lgkmcnt(8)
	v_mfma_f32_32x32x16_bf16 v[50:65], v[86:89], v[66:69], v[50:65]
	v_add_u32_e32 v0, s2, v149
	ds_read_b128 v[220:223], v0 offset:24576
	ds_read_b128 v[224:227], v0 offset:28672
	s_add_i32 s18, s3, 0xc0
	s_add_i32 s19, s10, 64
	s_cmp_eq_u32 s11, 0
	s_cselect_b32 s19, s18, s19
	s_add_i32 s18, s17, 3
	s_and_b32 s18, s18, 3
	s_lshl_b32 s18, s18, 15
	s_add_i32 s18, s13, s18
	v_mad_i64_i32 v[244:245], vcc, s19, v185, v[136:137]
	v_lshl_add_u64 v[246:247], v[244:245], 0, s[96:97]
	v_lshl_add_u64 v[244:245], v[244:245], 0, s[52:53]
	v_lshl_add_u64 v[248:249], v[138:139], 0, s[60:61]
	s_mov_b32 m0, s18
	v_mfma_f32_32x32x16_bf16 v[34:49], v[82:85], v[66:69], v[34:49]
	global_load_lds_dwordx4 v[246:247], off
	s_add_i32 m0, s18, 0x2000
	v_mfma_f32_32x32x16_bf16 v[18:33], v[78:81], v[66:69], v[18:33]
	v_mfma_f32_32x32x16_bf16 v[2:17], v[74:77], v[66:69], v[2:17]
	global_load_lds_dwordx4 v[244:245], off
	s_add_i32 m0, s18, 0x4000
	v_mfma_f32_32x32x16_bf16 v[50:65], v[126:129], v[70:73], v[50:65]
	ds_read_b128 v[126:129], v0 offset:20480
	v_mfma_f32_32x32x16_bf16 v[34:49], v[122:125], v[70:73], v[34:49]
	ds_read_b128 v[122:125], v0 offset:16384
	v_add_u32_e32 v0, s2, v146
	ds_read_b128 v[228:231], v0 offset:16384
	ds_read_b128 v[232:235], v0 offset:20480
	ds_read_b128 v[236:239], v0 offset:24576
	ds_read_b128 v[240:243], v0 offset:28672
	v_mfma_f32_32x32x16_bf16 v[18:33], v[94:97], v[70:73], v[18:33]
	v_mfma_f32_32x32x16_bf16 v[2:17], v[90:93], v[70:73], v[2:17]
	global_load_lds_dwordx4 v[248:249], off
	s_add_i32 m0, s18, 0x6000
	s_waitcnt lgkmcnt(8)
	v_mfma_f32_32x32x16_bf16 v[66:81], v[192:195], v[98:101], 0
	v_mfma_f32_32x32x16_bf16 v[82:97], v[154:157], v[98:101], 0
	v_mfma_f32_32x32x16_bf16 v[66:81], v[200:203], v[102:105], v[66:81]
	v_mfma_f32_32x32x16_bf16 v[82:97], v[196:199], v[102:105], v[82:97]
	global_load_lds_dwordx4 v[138:139], off
	v_mfma_f32_32x32x16_bf16 v[66:81], v[208:211], v[106:109], v[66:81]
	v_mfma_f32_32x32x16_bf16 v[82:97], v[204:207], v[106:109], v[82:97]
	v_mfma_f32_32x32x16_bf16 v[66:81], v[216:219], v[110:113], v[66:81]
	v_mfma_f32_32x32x16_bf16 v[82:97], v[212:215], v[110:113], v[82:97]
	s_waitcnt lgkmcnt(0)
; #define FENCE __builtin_amdgcn_sched_barrier(0)
; DI void diff_unit(KP p, int l, int b, int h, int qb, int isctx, float lamv, float lam_init, char* ldsc) {
;     ...
;     pv_grp(o, vA, P[2]);
;     const float mx = tile_max(st);
;     need = !__all(mx <= m + 8.0f);
;     const float mn = need ? fmaxf(m, mx) : m;
;     alpha = __builtin_amdgcn_exp2f(m - mn);
;     FENCE;
;     float ps = exp_pack1<0>(st, mn, P[0]);
;     ps += exp_pack1<1>(st, mn, P[1]);
;     ps += exp_pack1<2>(st, mn, P[2]);
;     pv_grp(o, vB, P[3]);
;     ps += exp_pack1<3>(st, mn, P[3]);
; #pragma unroll
;     for (int q = 0; q < 4; ++q) { __builtin_amdgcn_sched_group_barrier(0x402, 18, 0); __builtin_amdgcn_sched_group_barrier(0x008, 1, 0); }
;     lsum = lsum * alpha + ps; m = mn;
	v_mfma_f32_32x32x16_bf16 v[50:65], v[122:125], v[118:121], v[50:65]
	s_nop 9
	v_max3_f32 v0, v82, v83, v84
	v_max3_f32 v250, v66, v67, v68
	v_mfma_f32_32x32x16_bf16 v[34:49], v[126:129], v[118:121], v[34:49]
	v_max3_f32 v0, v0, v85, v86
	v_max3_f32 v250, v250, v69, v70
	v_max3_f32 v0, v0, v87, v88
	v_max3_f32 v250, v250, v71, v72
	v_max3_f32 v0, v0, v89, v90
	v_mfma_f32_32x32x16_bf16 v[18:33], v[220:223], v[118:121], v[18:33]
	v_max3_f32 v250, v250, v73, v74
	v_max3_f32 v0, v0, v91, v92
	v_max3_f32 v250, v250, v75, v76
	v_max3_f32 v0, v0, v93, v94
	v_max3_f32 v250, v250, v77, v78
	v_mfma_f32_32x32x16_bf16 v[2:17], v[224:227], v[118:121], v[2:17]
	v_max3_f32 v0, v0, v95, v96
	v_max3_f32 v250, v250, v79, v80
	v_max_f32_e32 v0, v0, v97
	v_max_f32_e32 v250, v250, v81
	v_max_f32_e32 v0, v0, v250
	v_mul_f32_e32 v0, 0x3e38aa3b, v0
	v_mov_b32_e32 v118, v0
	s_nop 1
	v_permlane32_swap_b32_e32 v0, v118
	v_max_f32_e32 v0, v0, v118
	v_add_f32_e32 v118, 0x41000000, v153
	v_cmp_le_f32_e32 vcc, v0, v118
	s_cmp_lg_u64 vcc, exec
	s_cselect_b64 s[4:5], -1, 0
	v_max_f32_e32 v0, v153, v0
	v_cndmask_b32_e64 v154, v153, v0, s[4:5]
	v_sub_f32_e32 v0, v153, v154
	v_exp_f32_e32 v140, v0
	v_fma_f32 v0, v82, s64, -v154
	v_exp_f32_e32 v122, v0
	v_fma_f32 v0, v83, s64, -v154
	v_exp_f32_e32 v124, v0
	v_fma_f32 v0, v84, s64, -v154
	v_exp_f32_e32 v126, v0
	v_fma_f32 v0, v85, s64, -v154
	v_exp_f32_e32 v128, v0
	v_fma_f32 v0, v86, s64, -v154
	v_exp_f32_e32 v156, v0
	v_fma_f32 v0, v87, s64, -v154
	v_exp_f32_e32 v192, v0
	v_fma_f32 v0, v88, s64, -v154
	v_exp_f32_e32 v194, v0
	v_fma_f32 v0, v89, s64, -v154
	v_exp_f32_e32 v196, v0
	v_fma_f32 v0, v90, s64, -v154
	v_exp_f32_e32 v123, v0
	v_mfma_f32_32x32x16_bf16 v[50:65], v[228:231], v[114:117], v[50:65]
	v_fma_f32 v0, v91, s64, -v154
	v_exp_f32_e32 v125, v0
	v_fma_f32 v0, v92, s64, -v154
	v_exp_f32_e32 v127, v0
	v_fma_f32 v0, v93, s64, -v154
	v_exp_f32_e32 v129, v0
	v_fma_f32 v0, v94, s64, -v154
	v_exp_f32_e32 v157, v0
	v_fma_f32 v0, v95, s64, -v154
	v_exp_f32_e32 v193, v0
	v_fma_f32 v0, v96, s64, -v154
	v_exp_f32_e32 v195, v0
	v_fma_f32 v0, v97, s64, -v154
	v_exp_f32_e32 v197, v0
	v_fma_f32 v0, v66, s64, -v154
	v_exp_f32_e32 v83, v0
	v_fma_f32 v0, v67, s64, -v154
	v_exp_f32_e32 v67, v0
	v_mfma_f32_32x32x16_bf16 v[34:49], v[232:235], v[114:117], v[34:49]
	v_fma_f32 v0, v68, s64, -v154
	v_exp_f32_e32 v85, v0
	v_fma_f32 v0, v69, s64, -v154
	v_exp_f32_e32 v69, v0
	v_fma_f32 v0, v70, s64, -v154
	v_exp_f32_e32 v87, v0
	v_fma_f32 v0, v71, s64, -v154
	v_exp_f32_e32 v71, v0
	v_fma_f32 v0, v72, s64, -v154
	v_exp_f32_e32 v89, v0
	v_fma_f32 v0, v73, s64, -v154
	v_exp_f32_e32 v73, v0
	v_fma_f32 v0, v74, s64, -v154
	v_exp_f32_e32 v82, v0
	v_fma_f32 v0, v75, s64, -v154
	v_exp_f32_e32 v66, v0
	v_fma_f32 v0, v76, s64, -v154
	v_exp_f32_e32 v84, v0
	v_mfma_f32_32x32x16_bf16 v[18:33], v[236:239], v[114:117], v[18:33]
	v_fma_f32 v0, v77, s64, -v154
	v_exp_f32_e32 v68, v0
	v_fma_f32 v0, v78, s64, -v154
	v_exp_f32_e32 v86, v0
	v_fma_f32 v0, v79, s64, -v154
	v_exp_f32_e32 v70, v0
	v_fma_f32 v0, v80, s64, -v154
	v_exp_f32_e32 v88, v0
	v_fma_f32 v0, v81, s64, -v154
	v_exp_f32_e32 v72, v0
	v_mfma_f32_32x32x16_bf16 v[2:17], v[240:243], v[114:117], v[2:17]
	v_cvt_pk_bf16_f32 v118, v83, v67
	v_cvt_pk_bf16_f32 v114, v82, v66
	v_add_f32_e64 v66, v66, v82
	v_add_f32_e64 v67, v67, v83
	v_cvt_pk_bf16_f32 v119, v85, v69
	v_add_f32_e32 v66, v84, v66
	v_add_f32_e32 v67, v85, v67
	v_cvt_pk_bf16_f32 v120, v87, v71
	v_add_f32_e32 v66, v68, v66
	v_add_f32_e32 v67, v69, v67
	v_cvt_pk_bf16_f32 v121, v89, v73
	v_add_f32_e32 v66, v86, v66
	v_add_f32_e32 v67, v87, v67
	v_cvt_pk_bf16_f32 v115, v84, v68
	v_add_f32_e32 v66, v70, v66
	v_add_f32_e32 v67, v71, v67
	v_cvt_pk_bf16_f32 v116, v86, v70
	v_add_f32_e32 v66, v88, v66
	v_add_f32_e32 v67, v89, v67
	v_cvt_pk_bf16_f32 v117, v88, v72
	v_add_f32_e32 v90, v72, v66
	v_add_f32_e32 v91, v73, v67
	v_add_u32_e32 v0, s15, v150
	v_add_f32_e32 v92, v124, v122
	v_add_f32_e32 v93, v125, v123
	ds_read_b128 v[86:89], v0 offset:16384
	ds_read_b128 v[82:85], v0 offset:20480
	v_add_f32_e32 v92, v126, v92
	v_add_f32_e32 v93, v127, v93
	ds_read_b128 v[78:81], v0 offset:24576
	ds_read_b128 v[74:77], v0 offset:28672
	v_add_f32_e32 v92, v128, v92
	v_add_f32_e32 v93, v129, v93
	v_cvt_pk_bf16_f32 v66, v122, v124
	v_add_f32_e32 v92, v156, v92
	v_add_f32_e32 v93, v157, v93
	v_cvt_pk_bf16_f32 v67, v126, v128
	v_add_f32_e32 v92, v192, v92
	v_add_f32_e32 v93, v193, v93
	v_cvt_pk_bf16_f32 v70, v123, v125
	v_add_f32_e32 v92, v194, v92
	v_add_f32_e32 v93, v195, v93
	v_cvt_pk_bf16_f32 v71, v127, v129
	v_add_f32_e32 v92, v196, v92
	v_add_f32_e32 v93, v197, v93
	s_add_i32 s11, s11, 1
	v_add_f32_e32 v0, v92, v93
	v_add_f32_e32 v0, v91, v0
	v_add_f32_e32 v0, v90, v0
	v_add_u32_e32 v90, s15, v151
	ds_read_b128 v[126:129], v90 offset:16384
	ds_read_b128 v[122:125], v90 offset:20480
	ds_read_b128 v[94:97], v90 offset:24576
	ds_read_b128 v[90:93], v90 offset:28672
	s_add_i32 s10, s10, 64
	v_cvt_pk_bf16_f32 v68, v156, v192
	v_cvt_pk_bf16_f32 v69, v194, v196
	v_cvt_pk_bf16_f32 v72, v157, v193
	v_cvt_pk_bf16_f32 v73, v195, v197
	v_fma_f32 v152, v152, v140, v0
	s_cmpk_eq_i32 s11, 0x83
	v_lshl_add_u64 v[138:139], v[138:139], 0, s[46:47]
	s_cbranch_scc1 .LBB0_479
	v_mov_b32_e32 v153, v154
	s_mov_b32 s17, s16
	s_branch .LBB0_471
